# FFN-up phase: workgroups on odd XCDs start the tile loop 32x64 cycles later (de-phased epilogue write bursts)
# speedup vs baseline: 1.0075x; 1.0075x over previous
.LBB0_129:
	v_and_b32_e32 v13, 15, v12
	v_lshrrev_b32_e32 v12, 1, v12
	v_and_b32_e32 v12, 24, v12
	v_lshlrev_b32_e32 v18, 1, v12
	v_lshl_or_b32 v150, s36, 6, v13
	v_lshl_or_b32 v18, v13, 6, v18
	v_lshlrev_b32_e32 v13, 2, v13
	s_lshl_b32 s6, s36, 13
	v_and_b32_e32 v19, 32, v13
	v_readlane_b32 s52, v254, 14
	v_bitop3_b32 v20, v18, s6, v19 bitop3:0xde
	s_lshl_b32 s6, s25, 5
	v_mov_b32_e32 v135, v1
	v_readlane_b32 s53, v254, 15
	s_and_b32 s25, s6, 0x60
	s_add_i32 m0, s61, 0x18000
	v_lshl_add_u64 v[2:3], v[2:3], 0, s[84:85]
	v_lshl_add_u64 v[14:15], s[52:53], 0, v[134:135]
	v_mov_b32_e32 v133, v1
	s_lshl_b32 s6, s25, 7
	s_waitcnt vmcnt(2)
	s_barrier
	global_load_lds_dwordx4 v[2:3], off
	v_lshl_add_u64 v[2:3], v[4:5], 0, s[84:85]
	s_add_i32 m0, s61, 0x1a000
	s_add_i32 s65, s61, 0x8000
	s_add_i32 s66, s61, 0xa000
	v_lshl_add_u64 v[16:17], s[52:53], 0, v[132:133]
	v_bitop3_b32 v151, v18, s6, v19 bitop3:0xde
	global_load_lds_dwordx4 v[2:3], off
	v_lshl_add_u64 v[2:3], v[14:15], 0, s[84:85]
	s_mov_b32 m0, s65
	s_add_u32 s6, s54, 0x40080
	global_load_lds_dwordx4 v[2:3], off
	v_lshl_add_u64 v[2:3], v[16:17], 0, s[84:85]
	s_mov_b32 m0, s66
	s_addc_u32 s7, s55, 0
	global_load_lds_dwordx4 v[2:3], off
	s_add_i32 m0, s61, 0x1c000
	v_lshl_add_u64 v[2:3], s[6:7], 0, v[0:1]
	global_load_lds_dwordx4 v[2:3], off
	v_lshl_add_u64 v[2:3], s[6:7], 0, v[130:131]
	s_add_i32 m0, s61, 0x1e000
	s_cmpk_lt_u32 s24, 0x100
	global_load_lds_dwordx4 v[2:3], off
	v_lshlrev_b32_e32 v2, 14, v10
	v_and_b32_e32 v2, 0xffff8000, v2
	v_lshl_add_u32 v2, v9, 11, v2
	v_and_b32_e32 v3, 1, v10
	v_lshl_or_b32 v2, v3, 6, v2
	s_cselect_b64 s[42:43], -1, 0
	s_and_b32 s6, s24, 0xffffff00
	v_lshl_add_u32 v136, v11, 1, v2
	v_lshlrev_b32_e32 v2, 14, v6
	s_add_i32 s6, s6, 0
	v_and_b32_e32 v2, 0xffff8000, v2
	s_waitcnt vmcnt(6)
	s_add_i32 s6, s6, 0x20200
	v_lshl_add_u32 v2, v7, 11, v2
	v_and_b32_e32 v3, 1, v6
	v_add_u32_e32 v152, s6, v13
	v_lshl_or_b32 v2, v3, 6, v2
	v_readlane_b32 s6, v254, 12
	v_or_b32_e32 v153, s25, v12
	v_mov_b32_e32 v137, v1
	v_lshl_add_u32 v138, v8, 1, v2
	v_mov_b32_e32 v139, v1
	s_mov_b32 s67, 0
	v_add_u32_e32 v154, 0, v20
	v_readlane_b32 s36, v254, 9
	s_mov_b32 s37, s6
	s_barrier
	v_readlane_b32 s7, v254, 13
	v_readlane_b32 s98, v252, 0
	s_bitcmp0_b32 s98, 5
	s_cbranch_scc1 .Ldephase_ffn
	s_sleep 32
.Ldephase_ffn:
	s_branch .LBB0_132
.LBB0_130:
	s_mov_b64 s[52:53], 0
